# P3 hgrn_correct state chain: two (D,L) load sets in flight instead of load-wait-fma per step
# speedup vs baseline: 1.0202x; 1.0054x over previous
; __device__ __forceinline__ void hgrn_correct(Frame& F, int item) {
;     ...
;         f32x4 Lc[8], Dc[8];
;         {
;             const int im = item - seg;
;             const f32x4* Lp = (const f32x4*)F.LBUF + (size_t)(im * 8 + w) * 8 * 64 + lane; const float* Dp = F.DTOT + im * 128;
; #pragma unroll
;             for (int tc = 0; tc < 8; ++tc) { Dc[tc] = *(const f32x4*)(Dp + 16 * tc + 4 * quad); Lc[tc] = Lp[tc * 64]; }
;         }
;         for (int m = 0; m < seg; ++m) {
;             f32x4 Ln[8], Dn[8];
;             const int im = item - seg + (m + 1 < seg ? m + 1 : m);
;             const f32x4* Lp = (const f32x4*)F.LBUF + (size_t)(im * 8 + w) * 8 * 64 + lane; const float* Dp = F.DTOT + im * 128;
; #pragma unroll
;             for (int tc = 0; tc < 8; ++tc) { Dn[tc] = *(const f32x4*)(Dp + 16 * tc + 4 * quad); Ln[tc] = Lp[tc * 64]; }
; #pragma unroll
;             for (int tc = 0; tc < 8; ++tc) { S[tc] = Dc[tc] * S[tc] + Lc[tc]; Lc[tc] = Ln[tc]; Dc[tc] = Dn[tc]; }
;         }
.LBB0_567:
	s_mov_b32 s23, 0
	s_add_i32 s24, s22, 0
	s_lshl_b32 s26, s24, 3
	s_add_i32 s26, s26, s94
	s_lshl_b32 s24, s24, 7
	s_ashr_i32 s25, s24, 31
	s_ashr_i32 s27, s26, 31
	v_lshl_add_u64 v[204:205], s[24:25], 2, v[160:161]
	s_lshl_b64 s[24:25], s[26:27], 13
	v_lshl_add_u64 v[220:221], v[158:159], 0, s[24:25]
	v_add_co_u32_e32 v222, vcc, s17, v220
	s_nop 1
	v_addc_co_u32_e32 v223, vcc, 0, v221, vcc
	global_load_dwordx4 v[98:101], v[204:205], off
	global_load_dwordx4 v[94:97], v[204:205], off offset:64
	global_load_dwordx4 v[62:65], v[204:205], off offset:128
	global_load_dwordx4 v[58:61], v[204:205], off offset:192
	global_load_dwordx4 v[54:57], v[204:205], off offset:256
	global_load_dwordx4 v[46:49], v[204:205], off offset:320
	global_load_dwordx4 v[42:45], v[204:205], off offset:384
	global_load_dwordx4 v[38:41], v[204:205], off offset:448
	global_load_dwordx4 v[102:105], v[220:221], off
	global_load_dwordx4 v[106:109], v[220:221], off offset:1024
	global_load_dwordx4 v[114:117], v[220:221], off offset:2048
	global_load_dwordx4 v[110:113], v[220:221], off offset:3072
	global_load_dwordx4 v[118:121], v[222:223], off
	global_load_dwordx4 v[122:125], v[222:223], off offset:1024
	global_load_dwordx4 v[126:129], v[222:223], off offset:2048
	global_load_dwordx4 v[130:133], v[222:223], off offset:3072
	s_cmp_lt_u32 s14, 2
	s_cbranch_scc1 .Lp3c_loop
	s_add_i32 s24, s22, 1
	s_lshl_b32 s26, s24, 3
	s_add_i32 s26, s26, s94
	s_lshl_b32 s24, s24, 7
	s_ashr_i32 s25, s24, 31
	s_ashr_i32 s27, s26, 31
	v_lshl_add_u64 v[204:205], s[24:25], 2, v[160:161]
	s_lshl_b64 s[24:25], s[26:27], 13
	v_lshl_add_u64 v[220:221], v[158:159], 0, s[24:25]
	v_add_co_u32_e32 v222, vcc, s17, v220
	s_nop 1
	v_addc_co_u32_e32 v223, vcc, 0, v221, vcc
	global_load_dwordx4 v[168:171], v[204:205], off
	global_load_dwordx4 v[172:175], v[204:205], off offset:64
	global_load_dwordx4 v[176:179], v[204:205], off offset:128
	global_load_dwordx4 v[180:183], v[204:205], off offset:192
	global_load_dwordx4 v[184:187], v[204:205], off offset:256
	global_load_dwordx4 v[188:191], v[204:205], off offset:320
	global_load_dwordx4 v[192:195], v[204:205], off offset:384
	global_load_dwordx4 v[196:199], v[204:205], off offset:448
	global_load_dwordx4 v[134:137], v[220:221], off
	global_load_dwordx4 v[138:141], v[220:221], off offset:1024
	global_load_dwordx4 v[142:145], v[220:221], off offset:2048
	global_load_dwordx4 v[146:149], v[220:221], off offset:3072
	global_load_dwordx4 v[150:153], v[222:223], off
	global_load_dwordx4 v[200:203], v[222:223], off offset:1024
	global_load_dwordx4 v[212:215], v[222:223], off offset:2048
	global_load_dwordx4 v[216:219], v[222:223], off offset:3072
.Lp3c_loop:
	s_add_i32 s25, s23, 1
	s_cmp_lt_u32 s25, s14
	s_cbranch_scc1 .Lp3c_w16A
	s_waitcnt vmcnt(0)
	s_branch .Lp3c_fA
.Lp3c_w16A:
	s_waitcnt vmcnt(16)
.Lp3c_fA:
	v_pk_fma_f32 v[6:7], v[6:7], v[98:99], v[102:103]
	v_pk_fma_f32 v[36:37], v[36:37], v[100:101], v[104:105]
	v_pk_fma_f32 v[32:33], v[32:33], v[94:95], v[106:107]
	v_pk_fma_f32 v[34:35], v[34:35], v[96:97], v[108:109]
	v_pk_fma_f32 v[26:27], v[26:27], v[62:63], v[114:115]
	v_pk_fma_f32 v[30:31], v[30:31], v[64:65], v[116:117]
	v_pk_fma_f32 v[24:25], v[24:25], v[58:59], v[110:111]
	v_pk_fma_f32 v[28:29], v[28:29], v[60:61], v[112:113]
	v_pk_fma_f32 v[18:19], v[18:19], v[54:55], v[118:119]
	v_pk_fma_f32 v[22:23], v[22:23], v[56:57], v[120:121]
	v_pk_fma_f32 v[16:17], v[16:17], v[46:47], v[122:123]
	v_pk_fma_f32 v[20:21], v[20:21], v[48:49], v[124:125]
	v_pk_fma_f32 v[10:11], v[10:11], v[42:43], v[126:127]
	v_pk_fma_f32 v[14:15], v[14:15], v[44:45], v[128:129]
	v_pk_fma_f32 v[8:9], v[8:9], v[38:39], v[130:131]
	v_pk_fma_f32 v[12:13], v[12:13], v[40:41], v[132:133]
	s_add_i32 s23, s23, 1
	s_cmp_eq_u32 s23, s14
	s_cbranch_scc1 .Lp3c_done
	s_add_i32 s25, s23, 1
	s_cmp_lt_u32 s25, s14
	s_cbranch_scc0 .Lp3c_skipA
	s_add_i32 s24, s22, s25
	s_lshl_b32 s26, s24, 3
	s_add_i32 s26, s26, s94
	s_lshl_b32 s24, s24, 7
	s_ashr_i32 s25, s24, 31
	s_ashr_i32 s27, s26, 31
	v_lshl_add_u64 v[204:205], s[24:25], 2, v[160:161]
	s_lshl_b64 s[24:25], s[26:27], 13
	v_lshl_add_u64 v[220:221], v[158:159], 0, s[24:25]
	v_add_co_u32_e32 v222, vcc, s17, v220
	s_nop 1
	v_addc_co_u32_e32 v223, vcc, 0, v221, vcc
	global_load_dwordx4 v[98:101], v[204:205], off
	global_load_dwordx4 v[94:97], v[204:205], off offset:64
	global_load_dwordx4 v[62:65], v[204:205], off offset:128
	global_load_dwordx4 v[58:61], v[204:205], off offset:192
	global_load_dwordx4 v[54:57], v[204:205], off offset:256
	global_load_dwordx4 v[46:49], v[204:205], off offset:320
	global_load_dwordx4 v[42:45], v[204:205], off offset:384
	global_load_dwordx4 v[38:41], v[204:205], off offset:448
	global_load_dwordx4 v[102:105], v[220:221], off
	global_load_dwordx4 v[106:109], v[220:221], off offset:1024
	global_load_dwordx4 v[114:117], v[220:221], off offset:2048
	global_load_dwordx4 v[110:113], v[220:221], off offset:3072
	global_load_dwordx4 v[118:121], v[222:223], off
	global_load_dwordx4 v[122:125], v[222:223], off offset:1024
	global_load_dwordx4 v[126:129], v[222:223], off offset:2048
	global_load_dwordx4 v[130:133], v[222:223], off offset:3072

; __device__ __forceinline__ unsigned cvt_pk_native(float lo, float hi) { f32x2 v = {lo, hi}; return __builtin_bit_cast(unsigned, __builtin_convertvector(v, nbf16x2)); }
; #define LAS __attribute__((address_space(3)))
; __device__ __forceinline__ void hgrn_correct(Frame& F, int item) {
;     ...
;         for (int m = 0; m < seg; ++m) {
;             f32x4 Ln[8], Dn[8];
;             const int im = item - seg + (m + 1 < seg ? m + 1 : m);
;             const f32x4* Lp = (const f32x4*)F.LBUF + (size_t)(im * 8 + w) * 8 * 64 + lane; const float* Dp = F.DTOT + im * 128;
; #pragma unroll
;             for (int tc = 0; tc < 8; ++tc) { Dn[tc] = *(const f32x4*)(Dp + 16 * tc + 4 * quad); Ln[tc] = Lp[tc * 64]; }
; #pragma unroll
;             for (int tc = 0; tc < 8; ++tc) { S[tc] = Dc[tc] * S[tc] + Lc[tc]; Lc[tc] = Ln[tc]; Dc[tc] = Dn[tc]; }
;         }
; #pragma unroll
;         for (int tc = 0; tc < 8; ++tc) { v2u o; o.x = pg8::cvt_pk_native(S[tc][0], S[tc][1]); o.y = pg8::cvt_pk_native(S[tc][2], S[tc][3]);
;             *(LAS v2u*)(ST + (16 * w + l15) * ST_STRIDE + 16 * tc + 4 * quad) = o; }
.Lp3c_fB:
	v_pk_fma_f32 v[6:7], v[6:7], v[168:169], v[134:135]
	v_pk_fma_f32 v[36:37], v[36:37], v[170:171], v[136:137]
	v_pk_fma_f32 v[32:33], v[32:33], v[172:173], v[138:139]
	v_pk_fma_f32 v[34:35], v[34:35], v[174:175], v[140:141]
	v_pk_fma_f32 v[26:27], v[26:27], v[176:177], v[142:143]
	v_pk_fma_f32 v[30:31], v[30:31], v[178:179], v[144:145]
	v_pk_fma_f32 v[24:25], v[24:25], v[180:181], v[146:147]
	v_pk_fma_f32 v[28:29], v[28:29], v[182:183], v[148:149]
	v_pk_fma_f32 v[18:19], v[18:19], v[184:185], v[150:151]
	v_pk_fma_f32 v[22:23], v[22:23], v[186:187], v[152:153]
	v_pk_fma_f32 v[16:17], v[16:17], v[188:189], v[200:201]
	v_pk_fma_f32 v[20:21], v[20:21], v[190:191], v[202:203]
	v_pk_fma_f32 v[10:11], v[10:11], v[192:193], v[212:213]
	v_pk_fma_f32 v[14:15], v[14:15], v[194:195], v[214:215]
	v_pk_fma_f32 v[8:9], v[8:9], v[196:197], v[216:217]
	v_pk_fma_f32 v[12:13], v[12:13], v[198:199], v[218:219]
	s_add_i32 s23, s23, 1
	s_cmp_eq_u32 s23, s14
	s_cbranch_scc1 .Lp3c_done
	s_add_i32 s25, s23, 1
	s_cmp_lt_u32 s25, s14
	s_cbranch_scc0 .Lp3c_skipB
	s_add_i32 s24, s22, s25
	s_lshl_b32 s26, s24, 3
	s_add_i32 s26, s26, s94
	s_lshl_b32 s24, s24, 7
	s_ashr_i32 s25, s24, 31
	s_ashr_i32 s27, s26, 31
	v_lshl_add_u64 v[204:205], s[24:25], 2, v[160:161]
	s_lshl_b64 s[24:25], s[26:27], 13
	v_lshl_add_u64 v[220:221], v[158:159], 0, s[24:25]
	v_add_co_u32_e32 v222, vcc, s17, v220
	s_nop 1
	v_addc_co_u32_e32 v223, vcc, 0, v221, vcc
	global_load_dwordx4 v[168:171], v[204:205], off
	global_load_dwordx4 v[172:175], v[204:205], off offset:64
	global_load_dwordx4 v[176:179], v[204:205], off offset:128
	global_load_dwordx4 v[180:183], v[204:205], off offset:192
	global_load_dwordx4 v[184:187], v[204:205], off offset:256
	global_load_dwordx4 v[188:191], v[204:205], off offset:320
	global_load_dwordx4 v[192:195], v[204:205], off offset:384
	global_load_dwordx4 v[196:199], v[204:205], off offset:448
	global_load_dwordx4 v[134:137], v[220:221], off
	global_load_dwordx4 v[138:141], v[220:221], off offset:1024
	global_load_dwordx4 v[142:145], v[220:221], off offset:2048
	global_load_dwordx4 v[146:149], v[220:221], off offset:3072
	global_load_dwordx4 v[150:153], v[222:223], off
	global_load_dwordx4 v[200:203], v[222:223], off offset:1024
	global_load_dwordx4 v[212:215], v[222:223], off offset:2048
	global_load_dwordx4 v[216:219], v[222:223], off offset:3072
.Lp3c_skipB:
	s_branch .Lp3c_loop
.Lp3c_done:
	v_cvt_pk_bf16_f32 v6, v6, v7
	v_cvt_pk_bf16_f32 v7, v36, v37
	v_cvt_pk_bf16_f32 v32, v32, v33
	v_cvt_pk_bf16_f32 v33, v34, v35
	ds_write2_b64 v207, v[6:7], v[32:33] offset1:4
	v_cvt_pk_bf16_f32 v6, v26, v27
	v_cvt_pk_bf16_f32 v7, v30, v31
	v_cvt_pk_bf16_f32 v24, v24, v25
	v_cvt_pk_bf16_f32 v25, v28, v29
	ds_write2_b64 v207, v[6:7], v[24:25] offset0:8 offset1:12
	v_cvt_pk_bf16_f32 v6, v18, v19
	v_cvt_pk_bf16_f32 v7, v22, v23
	v_cvt_pk_bf16_f32 v16, v16, v17
	v_cvt_pk_bf16_f32 v17, v20, v21
	ds_write2_b64 v207, v[6:7], v[16:17] offset0:16 offset1:20
	v_cvt_pk_bf16_f32 v6, v10, v11
	v_cvt_pk_bf16_f32 v7, v14, v15
	v_cvt_pk_bf16_f32 v8, v8, v9
	v_cvt_pk_bf16_f32 v9, v12, v13
	ds_write2_b64 v207, v[6:7], v[8:9] offset0:24 offset1:28
	v_mov_b64_e32 v[6:7], s[8:9]
	s_branch .LBB0_549
